# slot quota 16 transpose items per wave in up-GEMM idle half-round
# baseline (speedup 1.0000x reference)
.LBB0_130:
	s_or_b64 exec, exec, s[0:1]
	s_load_dwordx2 s[0:1], s[92:93], 0x58
	s_load_dwordx2 s[2:3], s[92:93], 0xb8
	s_load_dwordx2 s[4:5], s[92:93], 0xc0
	s_load_dwordx2 s[6:7], s[92:93], 0xc8
	s_load_dwordx2 s[8:9], s[92:93], 0xd0
	s_load_dwordx2 s[10:11], s[92:93], 0xe8
	v_and_b32_e32 v74, 63, v154
	v_lshrrev_b32_e32 v75, 6, v154
	v_mul_u32_u24_e32 v75, 0x2100, v75
	v_lshrrev_b32_e32 v3, 5, v74
	v_and_b32_e32 v4, 31, v74
	v_lshlrev_b32_e32 v4, 2, v4
	v_lshrrev_b32_e32 v5, 3, v74
	v_and_b32_e32 v6, 7, v74
	v_mul_u32_u24_e32 v2, 264, v6
	v_add_u32_e32 v2, v2, v5
	v_lshl_add_u32 v2, v2, 2, v75
	v_lshlrev_b32_e32 v6, 4, v6
	v_mul_u32_u24_e32 v1, 132, v5
	v_add3_u32 v1, v1, v6, v75
	v_readfirstlane_b32 s13, v154
	s_lshr_b32 s13, s13, 6
	s_lshl_b32 s26, s96, 3
	s_add_u32 s13, s13, s26
	s_mov_b32 s12, s13
	s_waitcnt lgkmcnt(0)
	s_cmp_ge_u32 s12, 50176
	s_cbranch_scc1 .Ltra_done
	s_cmp_ge_u32 s12, 33280
	s_cselect_b32 s41, 1, 0
	s_cselect_b32 s26, 33280, 0
	s_sub_u32 s42, s12, s26
	s_cmp_ge_u32 s42, 12288
	s_cbranch_scc1 .Ltra_m2
	s_mul_i32 s43, s42, 43691
	s_lshr_b32 s43, s43, 24
	s_mul_i32 s26, s43, 384
	s_sub_u32 s44, s42, s26
	s_mov_b32 s14, s0
	s_mov_b32 s15, s1
	s_mov_b32 s36, 0xc000
	s_mov_b32 s37, 0x6000000
	s_mov_b32 s38, 0x0
	s_mov_b32 s39, 0x3000000
	s_mov_b32 s40, 0x1000
	s_branch .Ltra_dec_done1

.Ltra_loop:
	s_add_u32 s12, s12, 2048
	s_cmp_lt_u32 s12, 50176
	s_cselect_b32 s24, 1, 0
	s_cbranch_scc0 .Ltra_nonext8
	s_cmp_ge_u32 s12, 33280
	s_cselect_b32 s41, 1, 0
	s_cselect_b32 s26, 33280, 0
	s_sub_u32 s42, s12, s26
	s_cmp_ge_u32 s42, 12288
	s_cbranch_scc1 .Ltra_m11
	s_mul_i32 s43, s42, 43691
	s_lshr_b32 s43, s43, 24
	s_mul_i32 s26, s43, 384
	s_sub_u32 s44, s42, s26
	s_mov_b32 s16, s0
	s_mov_b32 s17, s1
	s_mov_b32 s36, 0xc000
	s_mov_b32 s37, 0x6000000
	s_mov_b32 s38, 0x0
	s_mov_b32 s39, 0x3000000
	s_mov_b32 s40, 0x1000
	s_branch .Ltra_dec_done10

.Ltra_after9:
	ds_write_b32 v1, v10 offset:0
	ds_write_b32 v1, v11 offset:4
	ds_write_b32 v1, v12 offset:8
	ds_write_b32 v1, v13 offset:12
	ds_write_b32 v1, v14 offset:1056
	ds_write_b32 v1, v15 offset:1060
	ds_write_b32 v1, v16 offset:1064
	ds_write_b32 v1, v17 offset:1068
	ds_write_b32 v1, v18 offset:2112
	ds_write_b32 v1, v19 offset:2116
	ds_write_b32 v1, v20 offset:2120
	ds_write_b32 v1, v21 offset:2124
	ds_write_b32 v1, v22 offset:3168
	ds_write_b32 v1, v23 offset:3172
	ds_write_b32 v1, v24 offset:3176
	ds_write_b32 v1, v25 offset:3180
	ds_write_b32 v1, v26 offset:4224
	ds_write_b32 v1, v27 offset:4228
	ds_write_b32 v1, v28 offset:4232
	ds_write_b32 v1, v29 offset:4236
	ds_write_b32 v1, v30 offset:5280
	ds_write_b32 v1, v31 offset:5284
	ds_write_b32 v1, v32 offset:5288
	ds_write_b32 v1, v33 offset:5292
	ds_write_b32 v1, v34 offset:6336
	ds_write_b32 v1, v35 offset:6340
	ds_write_b32 v1, v36 offset:6344
	ds_write_b32 v1, v37 offset:6348
	ds_write_b32 v1, v38 offset:7392
	ds_write_b32 v1, v39 offset:7396
	ds_write_b32 v1, v40 offset:7400
	ds_write_b32 v1, v41 offset:7404
	v_mad_u32_u24 v9, v5, s22, v6
	s_lshl_b32 s46, s22, 3
	s_waitcnt lgkmcnt(0)
	ds_read_b32 v74, v2 offset:0
	ds_read_b32 v75, v2 offset:132
	ds_read_b32 v76, v2 offset:264
	ds_read_b32 v77, v2 offset:396
	ds_read_b32 v78, v2 offset:528
	ds_read_b32 v79, v2 offset:660
	ds_read_b32 v80, v2 offset:792
	ds_read_b32 v81, v2 offset:924
	ds_read_b32 v82, v2 offset:32
	ds_read_b32 v83, v2 offset:164
	ds_read_b32 v84, v2 offset:296
	ds_read_b32 v85, v2 offset:428
	ds_read_b32 v86, v2 offset:560
	ds_read_b32 v87, v2 offset:692
	ds_read_b32 v88, v2 offset:824
	ds_read_b32 v89, v2 offset:956
	s_waitcnt lgkmcnt(8)
	v_cvt_pk_bf16_f32 v106, v74, v75
	v_cvt_pk_bf16_f32 v107, v76, v77
	v_cvt_pk_bf16_f32 v108, v78, v79
	v_cvt_pk_bf16_f32 v109, v80, v81
	global_store_dwordx4 v9, v[106:109], s[18:19]
	s_add_u32 s18, s18, s46
	s_addc_u32 s19, s19, 0
	ds_read_b32 v90, v2 offset:64
	ds_read_b32 v91, v2 offset:196
	ds_read_b32 v92, v2 offset:328
	ds_read_b32 v93, v2 offset:460
	ds_read_b32 v94, v2 offset:592
	ds_read_b32 v95, v2 offset:724
	ds_read_b32 v96, v2 offset:856
	ds_read_b32 v97, v2 offset:988
	s_waitcnt lgkmcnt(8)
	v_cvt_pk_bf16_f32 v110, v82, v83
	v_cvt_pk_bf16_f32 v111, v84, v85
	v_cvt_pk_bf16_f32 v112, v86, v87
	v_cvt_pk_bf16_f32 v113, v88, v89
	global_store_dwordx4 v9, v[110:113], s[18:19]
	s_add_u32 s18, s18, s46
	s_addc_u32 s19, s19, 0
	ds_read_b32 v98, v2 offset:96
	ds_read_b32 v99, v2 offset:228
	ds_read_b32 v100, v2 offset:360
	ds_read_b32 v101, v2 offset:492
	ds_read_b32 v102, v2 offset:624
	ds_read_b32 v103, v2 offset:756
	ds_read_b32 v104, v2 offset:888
	ds_read_b32 v105, v2 offset:1020
	s_waitcnt lgkmcnt(8)
	v_cvt_pk_bf16_f32 v106, v90, v91
	v_cvt_pk_bf16_f32 v107, v92, v93
	v_cvt_pk_bf16_f32 v108, v94, v95
	v_cvt_pk_bf16_f32 v109, v96, v97
	global_store_dwordx4 v9, v[106:109], s[18:19]
	s_add_u32 s18, s18, s46
	s_addc_u32 s19, s19, 0
	s_waitcnt lgkmcnt(0)
	v_cvt_pk_bf16_f32 v110, v98, v99
	v_cvt_pk_bf16_f32 v111, v100, v101
	v_cvt_pk_bf16_f32 v112, v102, v103
	v_cvt_pk_bf16_f32 v113, v104, v105
	global_store_dwordx4 v9, v[110:113], s[18:19]
	s_cmp_eq_u32 s24, 0
	s_cbranch_scc1 .Ltra_done
	s_add_u32 s12, s12, 2048
	s_cmp_lt_u32 s12, 50176
	s_cselect_b32 s24, 1, 0
	s_cbranch_scc0 .Ltra_nonext17
	s_cmp_ge_u32 s12, 33280
	s_cselect_b32 s41, 1, 0
	s_cselect_b32 s26, 33280, 0
	s_sub_u32 s42, s12, s26
	s_cmp_ge_u32 s42, 12288
	s_cbranch_scc1 .Ltra_m20
	s_mul_i32 s43, s42, 43691
	s_lshr_b32 s43, s43, 24
	s_mul_i32 s26, s43, 384
	s_sub_u32 s44, s42, s26
	s_mov_b32 s14, s0
	s_mov_b32 s15, s1
	s_mov_b32 s36, 0xc000
	s_mov_b32 s37, 0x6000000
	s_mov_b32 s38, 0x0
	s_mov_b32 s39, 0x3000000
	s_mov_b32 s40, 0x1000
	s_branch .Ltra_dec_done19

.LBB0_1179:
	s_waitcnt vmcnt(0)
	s_barrier
	s_cmp_lt_u32 s96, 128
	s_cbranch_scc1 .LBB0_1180
	s_load_dwordx2 s[0:1], s[92:93], 0x58
	s_load_dwordx2 s[2:3], s[92:93], 0xb8
	s_load_dwordx2 s[4:5], s[92:93], 0xc0
	s_load_dwordx2 s[6:7], s[92:93], 0xc8
	s_load_dwordx2 s[8:9], s[92:93], 0xd0
	s_load_dwordx2 s[10:11], s[92:93], 0xe8
	v_and_b32_e32 v74, 63, v154
	v_lshrrev_b32_e32 v75, 6, v154
	v_mul_u32_u24_e32 v75, 0x2100, v75
	v_lshrrev_b32_e32 v3, 5, v74
	v_and_b32_e32 v4, 31, v74
	v_lshlrev_b32_e32 v4, 2, v4
	v_lshrrev_b32_e32 v5, 3, v74
	v_and_b32_e32 v6, 7, v74
	v_mul_u32_u24_e32 v2, 264, v6
	v_add_u32_e32 v2, v2, v5
	v_lshl_add_u32 v2, v2, 2, v75
	v_lshlrev_b32_e32 v6, 4, v6
	v_mul_u32_u24_e32 v1, 132, v5
	v_add3_u32 v1, v1, v6, v75
	v_readfirstlane_b32 s13, v154
	s_lshr_b32 s13, s13, 6
	s_lshl_b32 s26, s96, 3
	s_add_u32 s13, s13, s26
	s_sub_u32 s12, s13, 1024
	s_add_u32 s12, s12, 50176
	s_waitcnt lgkmcnt(0)
	s_cmp_ge_u32 s12, 66560
	s_cbranch_scc1 .Ltrs_done
	s_cmp_ge_u32 s12, 33280
	s_cselect_b32 s41, 1, 0
	s_cselect_b32 s26, 33280, 0
	s_sub_u32 s42, s12, s26
	s_cmp_ge_u32 s42, 12288
	s_cbranch_scc1 .Ltrs_m2
	s_mul_i32 s43, s42, 43691
	s_lshr_b32 s43, s43, 24
	s_mul_i32 s26, s43, 384
	s_sub_u32 s44, s42, s26
	s_mov_b32 s14, s0
	s_mov_b32 s15, s1
	s_mov_b32 s36, 0xc000
	s_mov_b32 s37, 0x6000000
	s_mov_b32 s38, 0x0
	s_mov_b32 s39, 0x3000000
	s_mov_b32 s40, 0x1000
	s_branch .Ltrs_dec_done1
